# stack: merged read-slot waits (v115) + 64-byte aligned K-loop heads (v114) on v113
# speedup vs baseline: 1.0031x; 1.0031x over previous
.LBB0_187:
	s_ashr_i32 s15, s14, 31
	s_lshl_b64 s[16:17], s[14:15], 19
	s_add_u32 s16, s30, s16
	s_addc_u32 s17, s31, s17
	s_and_b64 s[18:19], s[0:1], exec
	s_cselect_b32 s3, s17, s25
	s_cselect_b32 s15, s16, s24
	s_ashr_i32 s13, s12, 31
	s_lshl_b64 s[18:19], s[12:13], 19
	s_add_u32 s18, s34, s18
	s_addc_u32 s19, s35, s19
	s_and_b64 s[26:27], s[0:1], exec
	s_cselect_b32 s13, s19, s23
	s_cselect_b32 s21, s18, s22
	s_add_u32 s48, s22, 0x100
	s_addc_u32 s49, s23, 0
	s_add_u32 s22, s24, 0x40080
	s_addc_u32 s23, s25, 0
	s_mov_b32 s50, -2
	s_waitcnt vmcnt(0)
	s_add_u32 s24, s22, 0xfffc0080
	s_addc_u32 s25, s23, -1
	s_add_i32 s51, 0, 0x10000
	s_cmp_eq_u32 s50, 12
	s_cselect_b32 s27, s3, s25
	s_cselect_b32 s26, s15, s24
	v_add_u32_e32 v142, s51, v144
	s_cselect_b32 s25, s13, s49
	s_cselect_b32 s24, s21, s48
	s_add_i32 s54, 0, 0x14000
	ds_read_b128 v[138:141], v142
	ds_read_b128 v[146:149], v142 offset:1024
	ds_read_b128 v[150:153], v142 offset:2048
	ds_read_b128 v[154:157], v142 offset:3072
	v_add_u32_e32 v142, s54, v144
	ds_read_b128 v[158:161], v142
	ds_read_b128 v[162:165], v142 offset:1024
	ds_read_b128 v[166:169], v142 offset:2048
	ds_read_b128 v[170:173], v142 offset:3072
	v_lshl_add_u64 v[142:143], s[22:23], 0, v[136:137]
	s_add_i32 m0, s37, 0xc000
	ds_read_b128 v[174:177], v145
	ds_read_b128 v[178:181], v145 offset:1024
	ds_read_b128 v[182:185], v145 offset:2048
	ds_read_b128 v[186:189], v145 offset:3072
	ds_read_b128 v[190:193], v145 offset:4096
	ds_read_b128 v[194:197], v145 offset:5120
	ds_read_b128 v[198:201], v145 offset:6144
	ds_read_b128 v[202:205], v145 offset:7168
	global_load_lds_dwordx4 v[142:143], off
	v_lshl_add_u64 v[142:143], s[22:23], 0, v[134:135]
	s_add_i32 m0, s37, 0xe000
	s_nop 0
	global_load_lds_dwordx4 v[142:143], off
	s_waitcnt vmcnt(8) lgkmcnt(0)
	s_barrier
	v_mfma_f32_16x16x32_bf16 v[124:127], v[138:141], v[174:177], 0
	v_mfma_f32_16x16x32_bf16 v[120:123], v[150:153], v[174:177], 0
	v_mfma_f32_16x16x32_bf16 v[112:115], v[138:141], v[182:185], 0
	v_mfma_f32_16x16x32_bf16 v[104:107], v[150:153], v[182:185], 0
	v_mfma_f32_16x16x32_bf16 v[96:99], v[138:141], v[190:193], 0
	v_mfma_f32_16x16x32_bf16 v[88:91], v[150:153], v[190:193], 0
	v_mfma_f32_16x16x32_bf16 v[80:83], v[138:141], v[198:201], 0
	v_mfma_f32_16x16x32_bf16 v[72:75], v[150:153], v[198:201], 0
	v_mfma_f32_16x16x32_bf16 v[124:127], v[146:149], v[178:181], v[124:127]
	v_mfma_f32_16x16x32_bf16 v[120:123], v[154:157], v[178:181], v[120:123]
	v_mfma_f32_16x16x32_bf16 v[112:115], v[146:149], v[186:189], v[112:115]
	v_mfma_f32_16x16x32_bf16 v[104:107], v[154:157], v[186:189], v[104:107]
	v_mfma_f32_16x16x32_bf16 v[96:99], v[146:149], v[194:197], v[96:99]
	v_mfma_f32_16x16x32_bf16 v[88:91], v[154:157], v[194:197], v[88:91]
	v_mfma_f32_16x16x32_bf16 v[80:83], v[146:149], v[202:205], v[80:83]
	v_mfma_f32_16x16x32_bf16 v[72:75], v[154:157], v[202:205], v[72:75]
	v_mfma_f32_16x16x32_bf16 v[116:119], v[158:161], v[174:177], 0
	v_mfma_f32_16x16x32_bf16 v[108:111], v[166:169], v[174:177], 0
	v_mfma_f32_16x16x32_bf16 v[100:103], v[158:161], v[182:185], 0
	v_mfma_f32_16x16x32_bf16 v[92:95], v[166:169], v[182:185], 0
	v_mfma_f32_16x16x32_bf16 v[84:87], v[158:161], v[190:193], 0
	v_mfma_f32_16x16x32_bf16 v[76:79], v[166:169], v[190:193], 0
	v_mfma_f32_16x16x32_bf16 v[68:71], v[158:161], v[198:201], 0
	v_mfma_f32_16x16x32_bf16 v[64:67], v[166:169], v[198:201], 0
	v_mfma_f32_16x16x32_bf16 v[116:119], v[162:165], v[178:181], v[116:119]
	v_mfma_f32_16x16x32_bf16 v[108:111], v[170:173], v[178:181], v[108:111]
	v_mfma_f32_16x16x32_bf16 v[100:103], v[162:165], v[186:189], v[100:103]
	v_mfma_f32_16x16x32_bf16 v[92:95], v[170:173], v[186:189], v[92:95]
	v_mfma_f32_16x16x32_bf16 v[84:87], v[162:165], v[194:197], v[84:87]
	v_mfma_f32_16x16x32_bf16 v[76:79], v[170:173], v[194:197], v[76:79]
	v_mfma_f32_16x16x32_bf16 v[68:71], v[162:165], v[202:205], v[68:71]
	v_mfma_f32_16x16x32_bf16 v[64:67], v[170:173], v[202:205], v[64:67]
	s_barrier
	s_add_i32 s51, s51, s36
	v_lshl_add_u64 v[142:143], s[24:25], 0, v[232:233]
	s_mov_b32 m0, s51
	ds_read_b128 v[174:177], v145 offset:16384
	ds_read_b128 v[178:181], v145 offset:17408
	ds_read_b128 v[182:185], v145 offset:18432
	ds_read_b128 v[186:189], v145 offset:19456
	ds_read_b128 v[190:193], v145 offset:20480
	ds_read_b128 v[194:197], v145 offset:21504
	ds_read_b128 v[198:201], v145 offset:22528
	ds_read_b128 v[202:205], v145 offset:23552
	global_load_lds_dwordx4 v[142:143], off
	s_add_i32 m0, s51, 0x2000
	s_add_u32 s52, s24, 0x40000
	v_lshl_add_u64 v[206:207], s[24:25], 0, v[132:133]
	s_addc_u32 s53, s25, 0
	s_add_i32 s51, s54, s36
	global_load_lds_dwordx4 v[206:207], off
	v_lshl_add_u64 v[208:209], s[52:53], 0, v[232:233]
	s_mov_b32 m0, s51
	v_lshl_add_u64 v[210:211], s[26:27], 0, v[130:131]
	global_load_lds_dwordx4 v[208:209], off
	v_lshl_add_u64 v[208:209], s[52:53], 0, v[132:133]
	s_add_i32 m0, s51, 0x2000
	s_nop 0
	global_load_lds_dwordx4 v[208:209], off
	v_lshl_add_u64 v[208:209], s[26:27], 0, v[128:129]
	s_waitcnt vmcnt(6) lgkmcnt(0)
	s_barrier
	v_mfma_f32_16x16x32_bf16 v[60:63], v[138:141], v[174:177], 0
	v_mfma_f32_16x16x32_bf16 v[56:59], v[150:153], v[174:177], 0
	v_mfma_f32_16x16x32_bf16 v[48:51], v[138:141], v[182:185], 0
	v_mfma_f32_16x16x32_bf16 v[40:43], v[150:153], v[182:185], 0
	v_mfma_f32_16x16x32_bf16 v[32:35], v[138:141], v[190:193], 0
	v_mfma_f32_16x16x32_bf16 v[24:27], v[150:153], v[190:193], 0
	v_mfma_f32_16x16x32_bf16 v[16:19], v[138:141], v[198:201], 0
	v_mfma_f32_16x16x32_bf16 v[8:11], v[150:153], v[198:201], 0
	v_mfma_f32_16x16x32_bf16 v[60:63], v[146:149], v[178:181], v[60:63]
	v_mfma_f32_16x16x32_bf16 v[56:59], v[154:157], v[178:181], v[56:59]
	v_mfma_f32_16x16x32_bf16 v[48:51], v[146:149], v[186:189], v[48:51]
	v_mfma_f32_16x16x32_bf16 v[40:43], v[154:157], v[186:189], v[40:43]
	v_mfma_f32_16x16x32_bf16 v[32:35], v[146:149], v[194:197], v[32:35]
	v_mfma_f32_16x16x32_bf16 v[24:27], v[154:157], v[194:197], v[24:27]
	v_mfma_f32_16x16x32_bf16 v[16:19], v[146:149], v[202:205], v[16:19]
	v_mfma_f32_16x16x32_bf16 v[8:11], v[154:157], v[202:205], v[8:11]
	v_mfma_f32_16x16x32_bf16 v[52:55], v[158:161], v[174:177], 0
	v_mfma_f32_16x16x32_bf16 v[44:47], v[166:169], v[174:177], 0
	v_mfma_f32_16x16x32_bf16 v[36:39], v[158:161], v[182:185], 0
	v_mfma_f32_16x16x32_bf16 v[28:31], v[166:169], v[182:185], 0
	v_mfma_f32_16x16x32_bf16 v[20:23], v[158:161], v[190:193], 0
	v_mfma_f32_16x16x32_bf16 v[12:15], v[166:169], v[190:193], 0
	v_mfma_f32_16x16x32_bf16 v[4:7], v[158:161], v[198:201], 0
	v_mfma_f32_16x16x32_bf16 v[0:3], v[166:169], v[198:201], 0
	v_mfma_f32_16x16x32_bf16 v[52:55], v[162:165], v[178:181], v[52:55]
	v_mfma_f32_16x16x32_bf16 v[44:47], v[170:173], v[178:181], v[44:47]
	v_mfma_f32_16x16x32_bf16 v[36:39], v[162:165], v[186:189], v[36:39]
	v_mfma_f32_16x16x32_bf16 v[28:31], v[170:173], v[186:189], v[28:31]
	v_mfma_f32_16x16x32_bf16 v[20:23], v[162:165], v[194:197], v[20:23]
	v_mfma_f32_16x16x32_bf16 v[12:15], v[170:173], v[194:197], v[12:15]
	v_mfma_f32_16x16x32_bf16 v[4:7], v[162:165], v[202:205], v[4:7]
	v_mfma_f32_16x16x32_bf16 v[0:3], v[170:173], v[202:205], v[0:3]
	s_barrier
	s_branch .Lzmid_1
	.p2align 6

.LBB0_911:
	s_ashr_i32 s15, s14, 31
	s_lshl_b64 s[16:17], s[14:15], 19
	s_add_u32 s16, s30, s16
	s_addc_u32 s17, s31, s17
	s_and_b64 s[18:19], s[2:3], exec
	s_cselect_b32 s5, s17, s25
	s_cselect_b32 s15, s16, s24
	s_ashr_i32 s13, s12, 31
	s_lshl_b64 s[18:19], s[12:13], 19
	s_add_u32 s18, s34, s18
	s_addc_u32 s19, s35, s19
	s_and_b64 s[26:27], s[2:3], exec
	s_cselect_b32 s13, s19, s23
	s_cselect_b32 s21, s18, s22
	s_add_u32 s48, s22, 0x100
	s_addc_u32 s49, s23, 0
	s_add_u32 s22, s24, 0x40080
	s_addc_u32 s23, s25, 0
	s_mov_b32 s50, -2
	s_add_u32 s24, s22, 0xfffc0080
	s_addc_u32 s25, s23, -1
	s_add_i32 s51, 0, 0x10000
	s_cmp_eq_u32 s50, 12
	s_cselect_b32 s27, s5, s25
	s_cselect_b32 s26, s15, s24
	v_add_u32_e32 v142, s51, v144
	s_cselect_b32 s25, s13, s49
	s_cselect_b32 s24, s21, s48
	s_add_i32 s54, 0, 0x14000
	ds_read_b128 v[138:141], v142
	ds_read_b128 v[146:149], v142 offset:1024
	ds_read_b128 v[150:153], v142 offset:2048
	ds_read_b128 v[154:157], v142 offset:3072
	v_add_u32_e32 v142, s54, v144
	ds_read_b128 v[158:161], v142
	ds_read_b128 v[162:165], v142 offset:1024
	ds_read_b128 v[166:169], v142 offset:2048
	ds_read_b128 v[170:173], v142 offset:3072
	v_lshl_add_u64 v[142:143], s[22:23], 0, v[136:137]
	s_add_i32 m0, s37, 0xc000
	ds_read_b128 v[174:177], v145
	ds_read_b128 v[178:181], v145 offset:1024
	ds_read_b128 v[182:185], v145 offset:2048
	ds_read_b128 v[186:189], v145 offset:3072
	ds_read_b128 v[190:193], v145 offset:4096
	ds_read_b128 v[194:197], v145 offset:5120
	ds_read_b128 v[198:201], v145 offset:6144
	ds_read_b128 v[202:205], v145 offset:7168
	global_load_lds_dwordx4 v[142:143], off
	v_lshl_add_u64 v[142:143], s[22:23], 0, v[134:135]
	s_add_i32 m0, s37, 0xe000
	s_nop 0
	global_load_lds_dwordx4 v[142:143], off
	s_waitcnt vmcnt(8) lgkmcnt(0)
	s_barrier
	v_mfma_f32_16x16x32_bf16 v[124:127], v[138:141], v[174:177], 0
	v_mfma_f32_16x16x32_bf16 v[120:123], v[150:153], v[174:177], 0
	v_mfma_f32_16x16x32_bf16 v[108:111], v[138:141], v[182:185], 0
	v_mfma_f32_16x16x32_bf16 v[104:107], v[150:153], v[182:185], 0
	v_mfma_f32_16x16x32_bf16 v[92:95], v[138:141], v[190:193], 0
	v_mfma_f32_16x16x32_bf16 v[88:91], v[150:153], v[190:193], 0
	v_mfma_f32_16x16x32_bf16 v[76:79], v[138:141], v[198:201], 0
	v_mfma_f32_16x16x32_bf16 v[72:75], v[150:153], v[198:201], 0
	v_mfma_f32_16x16x32_bf16 v[124:127], v[146:149], v[178:181], v[124:127]
	v_mfma_f32_16x16x32_bf16 v[120:123], v[154:157], v[178:181], v[120:123]
	v_mfma_f32_16x16x32_bf16 v[108:111], v[146:149], v[186:189], v[108:111]
	v_mfma_f32_16x16x32_bf16 v[104:107], v[154:157], v[186:189], v[104:107]
	v_mfma_f32_16x16x32_bf16 v[92:95], v[146:149], v[194:197], v[92:95]
	v_mfma_f32_16x16x32_bf16 v[88:91], v[154:157], v[194:197], v[88:91]
	v_mfma_f32_16x16x32_bf16 v[76:79], v[146:149], v[202:205], v[76:79]
	v_mfma_f32_16x16x32_bf16 v[72:75], v[154:157], v[202:205], v[72:75]
	v_mfma_f32_16x16x32_bf16 v[116:119], v[158:161], v[174:177], 0
	v_mfma_f32_16x16x32_bf16 v[112:115], v[166:169], v[174:177], 0
	v_mfma_f32_16x16x32_bf16 v[100:103], v[158:161], v[182:185], 0
	v_mfma_f32_16x16x32_bf16 v[96:99], v[166:169], v[182:185], 0
	v_mfma_f32_16x16x32_bf16 v[84:87], v[158:161], v[190:193], 0
	v_mfma_f32_16x16x32_bf16 v[80:83], v[166:169], v[190:193], 0
	v_mfma_f32_16x16x32_bf16 v[68:71], v[158:161], v[198:201], 0
	v_mfma_f32_16x16x32_bf16 v[64:67], v[166:169], v[198:201], 0
	v_mfma_f32_16x16x32_bf16 v[116:119], v[162:165], v[178:181], v[116:119]
	v_mfma_f32_16x16x32_bf16 v[112:115], v[170:173], v[178:181], v[112:115]
	v_mfma_f32_16x16x32_bf16 v[100:103], v[162:165], v[186:189], v[100:103]
	v_mfma_f32_16x16x32_bf16 v[96:99], v[170:173], v[186:189], v[96:99]
	v_mfma_f32_16x16x32_bf16 v[84:87], v[162:165], v[194:197], v[84:87]
	v_mfma_f32_16x16x32_bf16 v[80:83], v[170:173], v[194:197], v[80:83]
	v_mfma_f32_16x16x32_bf16 v[68:71], v[162:165], v[202:205], v[68:71]
	v_mfma_f32_16x16x32_bf16 v[64:67], v[170:173], v[202:205], v[64:67]
	s_barrier
	s_add_i32 s51, s51, s36
	v_lshl_add_u64 v[142:143], s[24:25], 0, v[232:233]
	s_mov_b32 m0, s51
	ds_read_b128 v[174:177], v145 offset:16384
	ds_read_b128 v[178:181], v145 offset:17408
	ds_read_b128 v[182:185], v145 offset:18432
	ds_read_b128 v[186:189], v145 offset:19456
	ds_read_b128 v[190:193], v145 offset:20480
	ds_read_b128 v[194:197], v145 offset:21504
	ds_read_b128 v[198:201], v145 offset:22528
	ds_read_b128 v[202:205], v145 offset:23552
	global_load_lds_dwordx4 v[142:143], off
	s_add_i32 m0, s51, 0x2000
	s_add_u32 s52, s24, 0x40000
	v_lshl_add_u64 v[206:207], s[24:25], 0, v[132:133]
	s_addc_u32 s53, s25, 0
	s_add_i32 s51, s54, s36
	global_load_lds_dwordx4 v[206:207], off
	v_lshl_add_u64 v[208:209], s[52:53], 0, v[232:233]
	s_mov_b32 m0, s51
	v_lshl_add_u64 v[210:211], s[26:27], 0, v[130:131]
	global_load_lds_dwordx4 v[208:209], off
	v_lshl_add_u64 v[208:209], s[52:53], 0, v[132:133]
	s_add_i32 m0, s51, 0x2000
	s_nop 0
	global_load_lds_dwordx4 v[208:209], off
	v_lshl_add_u64 v[208:209], s[26:27], 0, v[128:129]
	s_waitcnt vmcnt(6) lgkmcnt(0)
	s_barrier
	v_mfma_f32_16x16x32_bf16 v[60:63], v[138:141], v[174:177], 0
	v_mfma_f32_16x16x32_bf16 v[56:59], v[150:153], v[174:177], 0
	v_mfma_f32_16x16x32_bf16 v[44:47], v[138:141], v[182:185], 0
	v_mfma_f32_16x16x32_bf16 v[40:43], v[150:153], v[182:185], 0
	v_mfma_f32_16x16x32_bf16 v[28:31], v[138:141], v[190:193], 0
	v_mfma_f32_16x16x32_bf16 v[24:27], v[150:153], v[190:193], 0
	v_mfma_f32_16x16x32_bf16 v[12:15], v[138:141], v[198:201], 0
	v_mfma_f32_16x16x32_bf16 v[8:11], v[150:153], v[198:201], 0
	v_mfma_f32_16x16x32_bf16 v[60:63], v[146:149], v[178:181], v[60:63]
	v_mfma_f32_16x16x32_bf16 v[56:59], v[154:157], v[178:181], v[56:59]
	v_mfma_f32_16x16x32_bf16 v[44:47], v[146:149], v[186:189], v[44:47]
	v_mfma_f32_16x16x32_bf16 v[40:43], v[154:157], v[186:189], v[40:43]
	v_mfma_f32_16x16x32_bf16 v[28:31], v[146:149], v[194:197], v[28:31]
	v_mfma_f32_16x16x32_bf16 v[24:27], v[154:157], v[194:197], v[24:27]
	v_mfma_f32_16x16x32_bf16 v[12:15], v[146:149], v[202:205], v[12:15]
	v_mfma_f32_16x16x32_bf16 v[8:11], v[154:157], v[202:205], v[8:11]
	v_mfma_f32_16x16x32_bf16 v[52:55], v[158:161], v[174:177], 0
	v_mfma_f32_16x16x32_bf16 v[48:51], v[166:169], v[174:177], 0
	v_mfma_f32_16x16x32_bf16 v[36:39], v[158:161], v[182:185], 0
	v_mfma_f32_16x16x32_bf16 v[32:35], v[166:169], v[182:185], 0
	v_mfma_f32_16x16x32_bf16 v[20:23], v[158:161], v[190:193], 0
	v_mfma_f32_16x16x32_bf16 v[16:19], v[166:169], v[190:193], 0
	v_mfma_f32_16x16x32_bf16 v[4:7], v[158:161], v[198:201], 0
	v_mfma_f32_16x16x32_bf16 v[0:3], v[166:169], v[198:201], 0
	v_mfma_f32_16x16x32_bf16 v[52:55], v[162:165], v[178:181], v[52:55]
	v_mfma_f32_16x16x32_bf16 v[48:51], v[170:173], v[178:181], v[48:51]
	v_mfma_f32_16x16x32_bf16 v[36:39], v[162:165], v[186:189], v[36:39]
	v_mfma_f32_16x16x32_bf16 v[32:35], v[170:173], v[186:189], v[32:35]
	v_mfma_f32_16x16x32_bf16 v[20:23], v[162:165], v[194:197], v[20:23]
	v_mfma_f32_16x16x32_bf16 v[16:19], v[170:173], v[194:197], v[16:19]
	v_mfma_f32_16x16x32_bf16 v[4:7], v[162:165], v[202:205], v[4:7]
	v_mfma_f32_16x16x32_bf16 v[0:3], v[170:173], v[202:205], v[0:3]
	s_barrier
	s_branch .Lzmid_2
	.p2align 6

.LBB0_1163:
	s_ashr_i32 s23, s22, 31
	s_lshl_b64 s[24:25], s[22:23], 19
	s_add_u32 s24, s42, s24
	s_addc_u32 s25, s43, s25
	s_and_b64 s[26:27], s[4:5], exec
	s_cselect_b32 s23, s25, s35
	s_cselect_b32 s56, s24, s34
	s_ashr_i32 s21, s20, 31
	s_lshl_b64 s[26:27], s[20:21], 19
	s_add_u32 s26, s44, s26
	s_addc_u32 s27, s45, s27
	s_and_b64 s[36:37], s[4:5], exec
	s_cselect_b32 s21, s27, s31
	s_cselect_b32 s57, s26, s30
	s_add_u32 s58, s30, 0x100
	s_addc_u32 s59, s31, 0
	s_add_u32 s30, s34, 0x40080
	s_addc_u32 s31, s35, 0
	s_mov_b32 s60, -2
	s_waitcnt vmcnt(0)
	s_add_u32 s34, s30, 0xfffc0080
	s_addc_u32 s35, s31, -1
	s_add_i32 s61, 0, 0x10000
	s_cmp_eq_u32 s60, 12
	s_cselect_b32 s37, s23, s35
	s_cselect_b32 s36, s56, s34
	s_cselect_b32 s35, s21, s59
	s_cselect_b32 s34, s57, s58
	s_add_i32 s64, 0, 0x14000
	v_add_u32_e32 v140, s61, v174
	v_add_u32_e32 v166, s64, v174
	ds_read_b128 v[128:131], v140
	ds_read_b128 v[132:135], v140 offset:1024
	ds_read_b128 v[136:139], v140 offset:2048
	ds_read_b128 v[140:143], v140 offset:3072
	ds_read_b128 v[154:157], v166
	ds_read_b128 v[158:161], v166 offset:1024
	ds_read_b128 v[162:165], v166 offset:2048
	ds_read_b128 v[166:169], v166 offset:3072
	v_lshl_add_u64 v[204:205], s[30:31], 0, v[152:153]
	s_add_i32 m0, s29, 0xc000
	ds_read_b128 v[170:173], v175
	ds_read_b128 v[176:179], v175 offset:1024
	ds_read_b128 v[180:183], v175 offset:2048
	ds_read_b128 v[184:187], v175 offset:3072
	ds_read_b128 v[188:191], v175 offset:4096
	ds_read_b128 v[192:195], v175 offset:5120
	ds_read_b128 v[196:199], v175 offset:6144
	ds_read_b128 v[200:203], v175 offset:7168
	global_load_lds_dwordx4 v[204:205], off
	v_lshl_add_u64 v[204:205], s[30:31], 0, v[150:151]
	s_add_i32 m0, s29, 0xe000
	s_nop 0
	global_load_lds_dwordx4 v[204:205], off
	s_waitcnt vmcnt(8) lgkmcnt(0)
	s_barrier
	v_mfma_f32_16x16x32_bf16 v[124:127], v[128:131], v[170:173], 0
	v_mfma_f32_16x16x32_bf16 v[120:123], v[136:139], v[170:173], 0
	v_mfma_f32_16x16x32_bf16 v[108:111], v[128:131], v[180:183], 0
	v_mfma_f32_16x16x32_bf16 v[104:107], v[136:139], v[180:183], 0
	v_mfma_f32_16x16x32_bf16 v[92:95], v[128:131], v[188:191], 0
	v_mfma_f32_16x16x32_bf16 v[88:91], v[136:139], v[188:191], 0
	v_mfma_f32_16x16x32_bf16 v[80:83], v[128:131], v[196:199], 0
	v_mfma_f32_16x16x32_bf16 v[72:75], v[136:139], v[196:199], 0
	v_mfma_f32_16x16x32_bf16 v[124:127], v[132:135], v[176:179], v[124:127]
	v_mfma_f32_16x16x32_bf16 v[120:123], v[140:143], v[176:179], v[120:123]
	v_mfma_f32_16x16x32_bf16 v[108:111], v[132:135], v[184:187], v[108:111]
	v_mfma_f32_16x16x32_bf16 v[104:107], v[140:143], v[184:187], v[104:107]
	v_mfma_f32_16x16x32_bf16 v[92:95], v[132:135], v[192:195], v[92:95]
	v_mfma_f32_16x16x32_bf16 v[88:91], v[140:143], v[192:195], v[88:91]
	v_mfma_f32_16x16x32_bf16 v[80:83], v[132:135], v[200:203], v[80:83]
	v_mfma_f32_16x16x32_bf16 v[72:75], v[140:143], v[200:203], v[72:75]
	v_mfma_f32_16x16x32_bf16 v[116:119], v[154:157], v[170:173], 0
	v_mfma_f32_16x16x32_bf16 v[112:115], v[162:165], v[170:173], 0
	v_mfma_f32_16x16x32_bf16 v[100:103], v[154:157], v[180:183], 0
	v_mfma_f32_16x16x32_bf16 v[96:99], v[162:165], v[180:183], 0
	v_mfma_f32_16x16x32_bf16 v[84:87], v[154:157], v[188:191], 0
	v_mfma_f32_16x16x32_bf16 v[76:79], v[162:165], v[188:191], 0
	v_mfma_f32_16x16x32_bf16 v[68:71], v[154:157], v[196:199], 0
	v_mfma_f32_16x16x32_bf16 v[64:67], v[162:165], v[196:199], 0
	v_mfma_f32_16x16x32_bf16 v[116:119], v[158:161], v[176:179], v[116:119]
	v_mfma_f32_16x16x32_bf16 v[112:115], v[166:169], v[176:179], v[112:115]
	v_mfma_f32_16x16x32_bf16 v[100:103], v[158:161], v[184:187], v[100:103]
	v_mfma_f32_16x16x32_bf16 v[96:99], v[166:169], v[184:187], v[96:99]
	v_mfma_f32_16x16x32_bf16 v[84:87], v[158:161], v[192:195], v[84:87]
	v_mfma_f32_16x16x32_bf16 v[76:79], v[166:169], v[192:195], v[76:79]
	v_mfma_f32_16x16x32_bf16 v[68:71], v[158:161], v[200:203], v[68:71]
	v_mfma_f32_16x16x32_bf16 v[64:67], v[166:169], v[200:203], v[64:67]
	s_barrier
	s_add_i32 s61, s61, s41
	v_lshl_add_u64 v[204:205], s[34:35], 0, v[232:233]
	s_mov_b32 m0, s61
	ds_read_b128 v[170:173], v175 offset:16384
	ds_read_b128 v[176:179], v175 offset:17408
	ds_read_b128 v[180:183], v175 offset:18432
	ds_read_b128 v[184:187], v175 offset:19456
	ds_read_b128 v[188:191], v175 offset:20480
	ds_read_b128 v[192:195], v175 offset:21504
	ds_read_b128 v[196:199], v175 offset:22528
	ds_read_b128 v[200:203], v175 offset:23552
	global_load_lds_dwordx4 v[204:205], off
	s_add_i32 m0, s61, 0x2000
	s_add_u32 s62, s34, 0x40000
	v_lshl_add_u64 v[206:207], s[34:35], 0, v[148:149]
	s_addc_u32 s63, s35, 0
	s_add_i32 s61, s64, s41
	global_load_lds_dwordx4 v[206:207], off
	v_lshl_add_u64 v[208:209], s[62:63], 0, v[232:233]
	s_mov_b32 m0, s61
	v_lshl_add_u64 v[210:211], s[36:37], 0, v[146:147]
	global_load_lds_dwordx4 v[208:209], off
	v_lshl_add_u64 v[208:209], s[62:63], 0, v[148:149]
	s_add_i32 m0, s61, 0x2000
	s_nop 0
	global_load_lds_dwordx4 v[208:209], off
	v_lshl_add_u64 v[208:209], s[36:37], 0, v[144:145]
	s_waitcnt vmcnt(6) lgkmcnt(0)
	s_barrier
	v_mfma_f32_16x16x32_bf16 v[60:63], v[128:131], v[170:173], 0
	v_mfma_f32_16x16x32_bf16 v[56:59], v[136:139], v[170:173], 0
	v_mfma_f32_16x16x32_bf16 v[48:51], v[128:131], v[180:183], 0
	v_mfma_f32_16x16x32_bf16 v[40:43], v[136:139], v[180:183], 0
	v_mfma_f32_16x16x32_bf16 v[28:31], v[128:131], v[188:191], 0
	v_mfma_f32_16x16x32_bf16 v[24:27], v[136:139], v[188:191], 0
	v_mfma_f32_16x16x32_bf16 v[16:19], v[128:131], v[196:199], 0
	v_mfma_f32_16x16x32_bf16 v[8:11], v[136:139], v[196:199], 0
	v_mfma_f32_16x16x32_bf16 v[60:63], v[132:135], v[176:179], v[60:63]
	v_mfma_f32_16x16x32_bf16 v[56:59], v[140:143], v[176:179], v[56:59]
	v_mfma_f32_16x16x32_bf16 v[48:51], v[132:135], v[184:187], v[48:51]
	v_mfma_f32_16x16x32_bf16 v[40:43], v[140:143], v[184:187], v[40:43]
	v_mfma_f32_16x16x32_bf16 v[28:31], v[132:135], v[192:195], v[28:31]
	v_mfma_f32_16x16x32_bf16 v[24:27], v[140:143], v[192:195], v[24:27]
	v_mfma_f32_16x16x32_bf16 v[16:19], v[132:135], v[200:203], v[16:19]
	v_mfma_f32_16x16x32_bf16 v[8:11], v[140:143], v[200:203], v[8:11]
	v_mfma_f32_16x16x32_bf16 v[52:55], v[154:157], v[170:173], 0
	v_mfma_f32_16x16x32_bf16 v[44:47], v[162:165], v[170:173], 0
	v_mfma_f32_16x16x32_bf16 v[36:39], v[154:157], v[180:183], 0
	v_mfma_f32_16x16x32_bf16 v[32:35], v[162:165], v[180:183], 0
	v_mfma_f32_16x16x32_bf16 v[20:23], v[154:157], v[188:191], 0
	v_mfma_f32_16x16x32_bf16 v[12:15], v[162:165], v[188:191], 0
	v_mfma_f32_16x16x32_bf16 v[4:7], v[154:157], v[196:199], 0
	v_mfma_f32_16x16x32_bf16 v[0:3], v[162:165], v[196:199], 0
	v_mfma_f32_16x16x32_bf16 v[52:55], v[158:161], v[176:179], v[52:55]
	v_mfma_f32_16x16x32_bf16 v[44:47], v[166:169], v[176:179], v[44:47]
	v_mfma_f32_16x16x32_bf16 v[36:39], v[158:161], v[184:187], v[36:39]
	v_mfma_f32_16x16x32_bf16 v[32:35], v[166:169], v[184:187], v[32:35]
	v_mfma_f32_16x16x32_bf16 v[20:23], v[158:161], v[192:195], v[20:23]
	v_mfma_f32_16x16x32_bf16 v[12:15], v[166:169], v[192:195], v[12:15]
	v_mfma_f32_16x16x32_bf16 v[4:7], v[158:161], v[200:203], v[4:7]
	v_mfma_f32_16x16x32_bf16 v[0:3], v[166:169], v[200:203], v[0:3]
	s_barrier
	s_branch .Lzmid_3
	.p2align 6

.LBB0_1306:
	s_ashr_i32 s17, s16, 31
	s_lshl_b64 s[18:19], s[16:17], 19
	s_add_u32 s18, s34, s18
	s_addc_u32 s19, s35, s19
	s_and_b64 s[20:21], s[4:5], exec
	s_cselect_b32 s7, s19, s27
	s_cselect_b32 s17, s18, s26
	s_ashr_i32 s15, s14, 31
	s_lshl_b64 s[20:21], s[14:15], 19
	s_add_u32 s20, s36, s20
	s_addc_u32 s21, s37, s21
	s_and_b64 s[28:29], s[4:5], exec
	s_cselect_b32 s15, s21, s25
	s_cselect_b32 s23, s20, s24
	s_add_u32 s50, s24, 0x100
	s_addc_u32 s51, s25, 0
	s_add_u32 s24, s26, 0x40080
	s_addc_u32 s25, s27, 0
	s_mov_b32 s52, -2
	s_add_u32 s26, s24, 0xfffc0080
	s_addc_u32 s27, s25, -1
	s_add_i32 s53, 0, 0x10000
	s_cmp_eq_u32 s52, 12
	s_cselect_b32 s29, s7, s27
	s_cselect_b32 s28, s17, s26
	v_add_u32_e32 v142, s53, v144
	s_cselect_b32 s27, s15, s51
	s_cselect_b32 s26, s23, s50
	s_add_i32 s56, 0, 0x14000
	ds_read_b128 v[138:141], v142
	ds_read_b128 v[146:149], v142 offset:1024
	ds_read_b128 v[150:153], v142 offset:2048
	ds_read_b128 v[154:157], v142 offset:3072
	v_add_u32_e32 v142, s56, v144
	ds_read_b128 v[158:161], v142
	ds_read_b128 v[162:165], v142 offset:1024
	ds_read_b128 v[166:169], v142 offset:2048
	ds_read_b128 v[170:173], v142 offset:3072
	v_lshl_add_u64 v[142:143], s[24:25], 0, v[136:137]
	s_add_i32 m0, s39, 0xc000
	ds_read_b128 v[174:177], v145
	ds_read_b128 v[178:181], v145 offset:1024
	ds_read_b128 v[182:185], v145 offset:2048
	ds_read_b128 v[186:189], v145 offset:3072
	ds_read_b128 v[190:193], v145 offset:4096
	ds_read_b128 v[194:197], v145 offset:5120
	ds_read_b128 v[198:201], v145 offset:6144
	ds_read_b128 v[202:205], v145 offset:7168
	global_load_lds_dwordx4 v[142:143], off
	v_lshl_add_u64 v[142:143], s[24:25], 0, v[134:135]
	s_add_i32 m0, s39, 0xe000
	s_nop 0
	global_load_lds_dwordx4 v[142:143], off
	s_waitcnt vmcnt(8) lgkmcnt(0)
	s_barrier
	v_mfma_f32_16x16x32_bf16 v[124:127], v[138:141], v[174:177], 0
	v_mfma_f32_16x16x32_bf16 v[120:123], v[150:153], v[174:177], 0
	v_mfma_f32_16x16x32_bf16 v[108:111], v[138:141], v[182:185], 0
	v_mfma_f32_16x16x32_bf16 v[104:107], v[150:153], v[182:185], 0
	v_mfma_f32_16x16x32_bf16 v[92:95], v[138:141], v[190:193], 0
	v_mfma_f32_16x16x32_bf16 v[88:91], v[150:153], v[190:193], 0
	v_mfma_f32_16x16x32_bf16 v[76:79], v[138:141], v[198:201], 0
	v_mfma_f32_16x16x32_bf16 v[72:75], v[150:153], v[198:201], 0
	v_mfma_f32_16x16x32_bf16 v[124:127], v[146:149], v[178:181], v[124:127]
	v_mfma_f32_16x16x32_bf16 v[120:123], v[154:157], v[178:181], v[120:123]
	v_mfma_f32_16x16x32_bf16 v[108:111], v[146:149], v[186:189], v[108:111]
	v_mfma_f32_16x16x32_bf16 v[104:107], v[154:157], v[186:189], v[104:107]
	v_mfma_f32_16x16x32_bf16 v[92:95], v[146:149], v[194:197], v[92:95]
	v_mfma_f32_16x16x32_bf16 v[88:91], v[154:157], v[194:197], v[88:91]
	v_mfma_f32_16x16x32_bf16 v[76:79], v[146:149], v[202:205], v[76:79]
	v_mfma_f32_16x16x32_bf16 v[72:75], v[154:157], v[202:205], v[72:75]
	v_mfma_f32_16x16x32_bf16 v[116:119], v[158:161], v[174:177], 0
	v_mfma_f32_16x16x32_bf16 v[112:115], v[166:169], v[174:177], 0
	v_mfma_f32_16x16x32_bf16 v[100:103], v[158:161], v[182:185], 0
	v_mfma_f32_16x16x32_bf16 v[96:99], v[166:169], v[182:185], 0
	v_mfma_f32_16x16x32_bf16 v[84:87], v[158:161], v[190:193], 0
	v_mfma_f32_16x16x32_bf16 v[80:83], v[166:169], v[190:193], 0
	v_mfma_f32_16x16x32_bf16 v[68:71], v[158:161], v[198:201], 0
	v_mfma_f32_16x16x32_bf16 v[64:67], v[166:169], v[198:201], 0
	v_mfma_f32_16x16x32_bf16 v[116:119], v[162:165], v[178:181], v[116:119]
	v_mfma_f32_16x16x32_bf16 v[112:115], v[170:173], v[178:181], v[112:115]
	v_mfma_f32_16x16x32_bf16 v[100:103], v[162:165], v[186:189], v[100:103]
	v_mfma_f32_16x16x32_bf16 v[96:99], v[170:173], v[186:189], v[96:99]
	v_mfma_f32_16x16x32_bf16 v[84:87], v[162:165], v[194:197], v[84:87]
	v_mfma_f32_16x16x32_bf16 v[80:83], v[170:173], v[194:197], v[80:83]
	v_mfma_f32_16x16x32_bf16 v[68:71], v[162:165], v[202:205], v[68:71]
	v_mfma_f32_16x16x32_bf16 v[64:67], v[170:173], v[202:205], v[64:67]
	s_barrier
	s_add_i32 s53, s53, s38
	v_lshl_add_u64 v[142:143], s[26:27], 0, v[232:233]
	s_mov_b32 m0, s53
	ds_read_b128 v[174:177], v145 offset:16384
	ds_read_b128 v[178:181], v145 offset:17408
	ds_read_b128 v[182:185], v145 offset:18432
	ds_read_b128 v[186:189], v145 offset:19456
	ds_read_b128 v[190:193], v145 offset:20480
	ds_read_b128 v[194:197], v145 offset:21504
	ds_read_b128 v[198:201], v145 offset:22528
	ds_read_b128 v[202:205], v145 offset:23552
	global_load_lds_dwordx4 v[142:143], off
	s_add_i32 m0, s53, 0x2000
	s_add_u32 s54, s26, 0x40000
	v_lshl_add_u64 v[206:207], s[26:27], 0, v[132:133]
	s_addc_u32 s55, s27, 0
	s_add_i32 s53, s56, s38
	global_load_lds_dwordx4 v[206:207], off
	v_lshl_add_u64 v[208:209], s[54:55], 0, v[232:233]
	s_mov_b32 m0, s53
	v_lshl_add_u64 v[210:211], s[28:29], 0, v[130:131]
	global_load_lds_dwordx4 v[208:209], off
	v_lshl_add_u64 v[208:209], s[54:55], 0, v[132:133]
	s_add_i32 m0, s53, 0x2000
	s_nop 0
	global_load_lds_dwordx4 v[208:209], off
	v_lshl_add_u64 v[208:209], s[28:29], 0, v[128:129]
	s_waitcnt vmcnt(6) lgkmcnt(0)
	s_barrier
	v_mfma_f32_16x16x32_bf16 v[60:63], v[138:141], v[174:177], 0
	v_mfma_f32_16x16x32_bf16 v[56:59], v[150:153], v[174:177], 0
	v_mfma_f32_16x16x32_bf16 v[44:47], v[138:141], v[182:185], 0
	v_mfma_f32_16x16x32_bf16 v[40:43], v[150:153], v[182:185], 0
	v_mfma_f32_16x16x32_bf16 v[28:31], v[138:141], v[190:193], 0
	v_mfma_f32_16x16x32_bf16 v[24:27], v[150:153], v[190:193], 0
	v_mfma_f32_16x16x32_bf16 v[12:15], v[138:141], v[198:201], 0
	v_mfma_f32_16x16x32_bf16 v[8:11], v[150:153], v[198:201], 0
	v_mfma_f32_16x16x32_bf16 v[60:63], v[146:149], v[178:181], v[60:63]
	v_mfma_f32_16x16x32_bf16 v[56:59], v[154:157], v[178:181], v[56:59]
	v_mfma_f32_16x16x32_bf16 v[44:47], v[146:149], v[186:189], v[44:47]
	v_mfma_f32_16x16x32_bf16 v[40:43], v[154:157], v[186:189], v[40:43]
	v_mfma_f32_16x16x32_bf16 v[28:31], v[146:149], v[194:197], v[28:31]
	v_mfma_f32_16x16x32_bf16 v[24:27], v[154:157], v[194:197], v[24:27]
	v_mfma_f32_16x16x32_bf16 v[12:15], v[146:149], v[202:205], v[12:15]
	v_mfma_f32_16x16x32_bf16 v[8:11], v[154:157], v[202:205], v[8:11]
	v_mfma_f32_16x16x32_bf16 v[52:55], v[158:161], v[174:177], 0
	v_mfma_f32_16x16x32_bf16 v[48:51], v[166:169], v[174:177], 0
	v_mfma_f32_16x16x32_bf16 v[36:39], v[158:161], v[182:185], 0
	v_mfma_f32_16x16x32_bf16 v[32:35], v[166:169], v[182:185], 0
	v_mfma_f32_16x16x32_bf16 v[20:23], v[158:161], v[190:193], 0
	v_mfma_f32_16x16x32_bf16 v[16:19], v[166:169], v[190:193], 0
	v_mfma_f32_16x16x32_bf16 v[4:7], v[158:161], v[198:201], 0
	v_mfma_f32_16x16x32_bf16 v[0:3], v[166:169], v[198:201], 0
	v_mfma_f32_16x16x32_bf16 v[52:55], v[162:165], v[178:181], v[52:55]
	v_mfma_f32_16x16x32_bf16 v[48:51], v[170:173], v[178:181], v[48:51]
	v_mfma_f32_16x16x32_bf16 v[36:39], v[162:165], v[186:189], v[36:39]
	v_mfma_f32_16x16x32_bf16 v[32:35], v[170:173], v[186:189], v[32:35]
	v_mfma_f32_16x16x32_bf16 v[20:23], v[162:165], v[194:197], v[20:23]
	v_mfma_f32_16x16x32_bf16 v[16:19], v[170:173], v[194:197], v[16:19]
	v_mfma_f32_16x16x32_bf16 v[4:7], v[162:165], v[202:205], v[4:7]
	v_mfma_f32_16x16x32_bf16 v[0:3], v[170:173], v[202:205], v[0:3]
	s_barrier
	s_branch .Lzmid_4
	.p2align 6

.LBB0_1491:
	s_ashr_i32 s23, s22, 31
	s_lshl_b64 s[24:25], s[22:23], 21
	s_add_u32 s24, s70, s24
	s_addc_u32 s25, s71, s25
	s_and_b64 s[26:27], s[4:5], exec
	s_cselect_b32 s23, s25, s35
	s_cselect_b32 s56, s24, s34
	s_ashr_i32 s21, s20, 31
	s_lshl_b64 s[26:27], s[20:21], 21
	s_add_u32 s26, s72, s26
	s_addc_u32 s27, s76, s27
	s_and_b64 s[36:37], s[4:5], exec
	s_cselect_b32 s21, s27, s31
	s_cselect_b32 s57, s26, s30
	s_add_u32 s58, s30, 0x100
	s_addc_u32 s59, s31, 0
	s_add_u32 s30, s34, 0x100080
	s_addc_u32 s31, s35, 0
	s_mov_b32 s60, -2
	s_waitcnt vmcnt(0)
	s_add_u32 s34, s30, 0xfff00080
	s_addc_u32 s35, s31, -1
	s_add_i32 s61, 0, 0x10000
	s_cmp_eq_u32 s60, 60
	s_cselect_b32 s37, s23, s35
	s_cselect_b32 s36, s56, s34
	s_cselect_b32 s35, s21, s59
	s_cselect_b32 s34, s57, s58
	s_add_i32 s64, 0, 0x14000
	v_add_u32_e32 v100, s61, v220
	v_add_u32_e32 v156, s64, v220
	ds_read_b128 v[88:91], v100
	ds_read_b128 v[92:95], v100 offset:1024
	ds_read_b128 v[96:99], v100 offset:2048
	ds_read_b128 v[100:103], v100 offset:3072
	ds_read_b128 v[144:147], v156
	ds_read_b128 v[148:151], v156 offset:1024
	ds_read_b128 v[152:155], v156 offset:2048
	ds_read_b128 v[156:159], v156 offset:3072
	v_lshl_add_u64 v[202:203], s[30:31], 0, v[188:189]
	s_add_i32 m0, s78, 0xc000
	ds_read_b128 v[160:163], v221
	ds_read_b128 v[164:167], v221 offset:1024
	ds_read_b128 v[168:171], v221 offset:2048
	ds_read_b128 v[172:175], v221 offset:3072
	ds_read_b128 v[176:179], v221 offset:4096
	ds_read_b128 v[190:193], v221 offset:5120
	ds_read_b128 v[194:197], v221 offset:6144
	ds_read_b128 v[198:201], v221 offset:7168
	global_load_lds_dwordx4 v[202:203], off
	v_lshl_add_u64 v[202:203], s[30:31], 0, v[186:187]
	s_add_i32 m0, s78, 0xe000
	s_nop 0
	global_load_lds_dwordx4 v[202:203], off
	s_waitcnt vmcnt(8) lgkmcnt(0)
	s_barrier
	v_mfma_f32_16x16x32_bf16 v[140:143], v[88:91], v[160:163], 0
	v_mfma_f32_16x16x32_bf16 v[136:139], v[96:99], v[160:163], 0
	v_mfma_f32_16x16x32_bf16 v[124:127], v[88:91], v[168:171], 0
	v_mfma_f32_16x16x32_bf16 v[120:123], v[96:99], v[168:171], 0
	v_mfma_f32_16x16x32_bf16 v[108:111], v[88:91], v[176:179], 0
	v_mfma_f32_16x16x32_bf16 v[104:107], v[96:99], v[176:179], 0
	v_mfma_f32_16x16x32_bf16 v[76:79], v[88:91], v[194:197], 0
	v_mfma_f32_16x16x32_bf16 v[72:75], v[96:99], v[194:197], 0
	v_mfma_f32_16x16x32_bf16 v[140:143], v[92:95], v[164:167], v[140:143]
	v_mfma_f32_16x16x32_bf16 v[136:139], v[100:103], v[164:167], v[136:139]
	v_mfma_f32_16x16x32_bf16 v[124:127], v[92:95], v[172:175], v[124:127]
	v_mfma_f32_16x16x32_bf16 v[120:123], v[100:103], v[172:175], v[120:123]
	v_mfma_f32_16x16x32_bf16 v[108:111], v[92:95], v[190:193], v[108:111]
	v_mfma_f32_16x16x32_bf16 v[104:107], v[100:103], v[190:193], v[104:107]
	v_mfma_f32_16x16x32_bf16 v[76:79], v[92:95], v[198:201], v[76:79]
	v_mfma_f32_16x16x32_bf16 v[72:75], v[100:103], v[198:201], v[72:75]
	v_mfma_f32_16x16x32_bf16 v[132:135], v[144:147], v[160:163], 0
	v_mfma_f32_16x16x32_bf16 v[128:131], v[152:155], v[160:163], 0
	v_mfma_f32_16x16x32_bf16 v[116:119], v[144:147], v[168:171], 0
	v_mfma_f32_16x16x32_bf16 v[112:115], v[152:155], v[168:171], 0
	v_mfma_f32_16x16x32_bf16 v[84:87], v[144:147], v[176:179], 0
	v_mfma_f32_16x16x32_bf16 v[80:83], v[152:155], v[176:179], 0
	v_mfma_f32_16x16x32_bf16 v[68:71], v[144:147], v[194:197], 0
	v_mfma_f32_16x16x32_bf16 v[64:67], v[152:155], v[194:197], 0
	v_mfma_f32_16x16x32_bf16 v[132:135], v[148:151], v[164:167], v[132:135]
	v_mfma_f32_16x16x32_bf16 v[128:131], v[156:159], v[164:167], v[128:131]
	v_mfma_f32_16x16x32_bf16 v[116:119], v[148:151], v[172:175], v[116:119]
	v_mfma_f32_16x16x32_bf16 v[112:115], v[156:159], v[172:175], v[112:115]
	v_mfma_f32_16x16x32_bf16 v[84:87], v[148:151], v[190:193], v[84:87]
	v_mfma_f32_16x16x32_bf16 v[80:83], v[156:159], v[190:193], v[80:83]
	v_mfma_f32_16x16x32_bf16 v[68:71], v[148:151], v[198:201], v[68:71]
	v_mfma_f32_16x16x32_bf16 v[64:67], v[156:159], v[198:201], v[64:67]
	s_barrier
	s_add_i32 s61, s61, s77
	v_lshl_add_u64 v[202:203], s[34:35], 0, v[232:233]
	s_mov_b32 m0, s61
	ds_read_b128 v[160:163], v221 offset:16384
	ds_read_b128 v[164:167], v221 offset:17408
	ds_read_b128 v[168:171], v221 offset:18432
	ds_read_b128 v[172:175], v221 offset:19456
	ds_read_b128 v[176:179], v221 offset:20480
	ds_read_b128 v[190:193], v221 offset:21504
	ds_read_b128 v[194:197], v221 offset:22528
	ds_read_b128 v[198:201], v221 offset:23552
	global_load_lds_dwordx4 v[202:203], off
	s_add_i32 m0, s61, 0x2000
	s_add_u32 s62, s34, 0x100000
	v_lshl_add_u64 v[204:205], s[34:35], 0, v[184:185]
	s_addc_u32 s63, s35, 0
	s_add_i32 s61, s64, s77
	global_load_lds_dwordx4 v[204:205], off
	v_lshl_add_u64 v[206:207], s[62:63], 0, v[232:233]
	s_mov_b32 m0, s61
	v_lshl_add_u64 v[208:209], s[36:37], 0, v[182:183]
	global_load_lds_dwordx4 v[206:207], off
	v_lshl_add_u64 v[206:207], s[62:63], 0, v[184:185]
	s_add_i32 m0, s61, 0x2000
	s_nop 0
	global_load_lds_dwordx4 v[206:207], off
	v_lshl_add_u64 v[206:207], s[36:37], 0, v[180:181]
	s_waitcnt vmcnt(6) lgkmcnt(0)
	s_barrier
	v_mfma_f32_16x16x32_bf16 v[60:63], v[88:91], v[160:163], 0
	v_mfma_f32_16x16x32_bf16 v[56:59], v[96:99], v[160:163], 0
	v_mfma_f32_16x16x32_bf16 v[44:47], v[88:91], v[168:171], 0
	v_mfma_f32_16x16x32_bf16 v[40:43], v[96:99], v[168:171], 0
	v_mfma_f32_16x16x32_bf16 v[28:31], v[88:91], v[176:179], 0
	v_mfma_f32_16x16x32_bf16 v[24:27], v[96:99], v[176:179], 0
	v_mfma_f32_16x16x32_bf16 v[12:15], v[88:91], v[194:197], 0
	v_mfma_f32_16x16x32_bf16 v[8:11], v[96:99], v[194:197], 0
	v_mfma_f32_16x16x32_bf16 v[60:63], v[92:95], v[164:167], v[60:63]
	v_mfma_f32_16x16x32_bf16 v[56:59], v[100:103], v[164:167], v[56:59]
	v_mfma_f32_16x16x32_bf16 v[44:47], v[92:95], v[172:175], v[44:47]
	v_mfma_f32_16x16x32_bf16 v[40:43], v[100:103], v[172:175], v[40:43]
	v_mfma_f32_16x16x32_bf16 v[28:31], v[92:95], v[190:193], v[28:31]
	v_mfma_f32_16x16x32_bf16 v[24:27], v[100:103], v[190:193], v[24:27]
	v_mfma_f32_16x16x32_bf16 v[12:15], v[92:95], v[198:201], v[12:15]
	v_mfma_f32_16x16x32_bf16 v[8:11], v[100:103], v[198:201], v[8:11]
	v_mfma_f32_16x16x32_bf16 v[52:55], v[144:147], v[160:163], 0
	v_mfma_f32_16x16x32_bf16 v[48:51], v[152:155], v[160:163], 0
	v_mfma_f32_16x16x32_bf16 v[36:39], v[144:147], v[168:171], 0
	v_mfma_f32_16x16x32_bf16 v[32:35], v[152:155], v[168:171], 0
	v_mfma_f32_16x16x32_bf16 v[20:23], v[144:147], v[176:179], 0
	v_mfma_f32_16x16x32_bf16 v[16:19], v[152:155], v[176:179], 0
	v_mfma_f32_16x16x32_bf16 v[4:7], v[144:147], v[194:197], 0
	v_mfma_f32_16x16x32_bf16 v[0:3], v[152:155], v[194:197], 0
	v_mfma_f32_16x16x32_bf16 v[52:55], v[148:151], v[164:167], v[52:55]
	v_mfma_f32_16x16x32_bf16 v[48:51], v[156:159], v[164:167], v[48:51]
	v_mfma_f32_16x16x32_bf16 v[36:39], v[148:151], v[172:175], v[36:39]
	v_mfma_f32_16x16x32_bf16 v[32:35], v[156:159], v[172:175], v[32:35]
	v_mfma_f32_16x16x32_bf16 v[20:23], v[148:151], v[190:193], v[20:23]
	v_mfma_f32_16x16x32_bf16 v[16:19], v[156:159], v[190:193], v[16:19]
	v_mfma_f32_16x16x32_bf16 v[4:7], v[148:151], v[198:201], v[4:7]
	v_mfma_f32_16x16x32_bf16 v[0:3], v[156:159], v[198:201], v[0:3]
	s_barrier
	s_branch .Lzmid_6
	.p2align 6
